# v29: v15 + scan-phase roles segregated by XCD (GDN scan + helpers on XCDs 0-3, HGRN scan + conversion on XCDs 4-7) + sc1 nt on the conversion's f32 loads
# speedup vs baseline: 1.0069x; 1.0069x over previous
.LBB0_256:
	s_mov_b32 s100, s64
	s_and_b32 s98, s64, 3
	s_lshl_b32 s98, s98, 1
	s_bfe_u32 s99, s64, 0x10003
	s_or_b32 s98, s98, s99
	s_bfe_u32 s99, s64, 0x30004
	s_lshl_b32 s99, s99, 3
	s_or_b32 s98, s98, s99
	s_bfe_u32 s99, s64, 0x10002
	s_lshl_b32 s101, s99, 7
	s_sub_i32 s101, 0xc0, s101
	s_lshl_b32 s99, s99, 6
	s_add_i32 s98, s98, s99
	s_bfe_u32 s99, s64, 0x10007
	s_mul_i32 s99, s99, s101
	s_add_i32 s64, s98, s99
	v_readlane_b32 s8, v253, 41
	s_cmp_lt_i32 s66, 5
	v_readlane_b32 s22, v253, 55
	s_cselect_b64 s[4:5], -1, 0
	v_readlane_b32 s23, v253, 56
	s_add_u32 s28, s22, 0x2200000
	s_addc_u32 s29, s23, 0
	s_add_u32 s26, s22, 0x2a00000
	s_addc_u32 s27, s23, 0
	s_add_u32 s24, s22, 0x4a00000
	s_addc_u32 s25, s23, 0
	s_and_b64 s[30:31], s[4:5], s[2:3]
	s_andn2_b64 vcc, exec, s[30:31]
	v_readlane_b32 s9, v253, 42
	v_readlane_b32 s10, v253, 43
	v_readlane_b32 s11, v253, 44
	v_readlane_b32 s12, v253, 45
	v_readlane_b32 s13, v253, 46
	v_readlane_b32 s14, v253, 47
	v_readlane_b32 s15, v253, 48
	v_readlane_b32 s16, v253, 49
	v_readlane_b32 s17, v253, 50
	v_readlane_b32 s18, v253, 51
	v_readlane_b32 s19, v253, 52
	v_readlane_b32 s20, v253, 53
	v_readlane_b32 s21, v253, 54
	s_cbranch_vccnz .LBB0_377
	s_and_b32 s2, s64, 0xffffffc0
	s_cmpk_lg_i32 s2, 0x80
	s_cbranch_scc1 .LBB0_303
	s_lshl_b32 s2, s64, 3
	s_add_i32 s2, s2, s91
	s_add_i32 s41, s2, 0xfffffc00
	s_cmpk_lt_i32 s41, 0x4800
	s_cselect_b64 s[18:19], -1, 0
	s_and_b64 vcc, exec, s[18:19]
	v_lshrrev_b32_e32 v1, 5, v170
	v_and_b32_e32 v52, 31, v0
	s_cbranch_vccnz .LBB0_261
	v_lshrrev_b32_e32 v53, 5, v170
	v_and_b32_e32 v42, 31, v0
	v_mov_b32_e32 v43, 0
	s_cbranch_execz .LBB0_262
	s_waitcnt vmcnt(0)
	v_mov_b32_e32 v2, 0
	v_mov_b32_e32 v3, v2
	v_mov_b32_e32 v4, v2
	v_mov_b32_e32 v5, v2
	v_mov_b32_e32 v6, v2
	v_mov_b32_e32 v7, v2
	v_mov_b32_e32 v8, v2
	v_mov_b32_e32 v9, v2
	v_mov_b32_e32 v44, v2
	v_mov_b32_e32 v45, v2
	v_mov_b32_e32 v46, v2
	v_mov_b32_e32 v47, v2
	v_mov_b32_e32 v48, v2
	v_mov_b32_e32 v49, v2
	v_mov_b32_e32 v50, v2
	v_mov_b32_e32 v51, v2
	v_mov_b32_e32 v56, v2
	v_mov_b32_e32 v57, v2
	v_mov_b32_e32 v58, v2
	v_mov_b32_e32 v59, v2
	v_mov_b32_e32 v60, v2
	v_mov_b32_e32 v61, v2
	v_mov_b32_e32 v94, v2
	v_mov_b32_e32 v95, v2
	v_mov_b32_e32 v96, v2
	v_mov_b32_e32 v97, v2
	v_mov_b32_e32 v98, v2
	v_mov_b32_e32 v99, v2
	v_mov_b32_e32 v100, v2
	v_mov_b32_e32 v101, v2
	v_mov_b32_e32 v102, v2
	v_mov_b32_e32 v103, v2
	v_mov_b32_e32 v1, v53
	v_mov_b32_e32 v52, v42
	s_branch .LBB0_272

.LBB0_268:
	s_mov_b32 s5, 0
	s_lshl_b64 s[14:15], s[4:5], 2
	s_add_u32 s12, s12, s14
	s_waitcnt vmcnt(0)
	v_add_u32_e32 v10, s2, v1
	v_mov_b32_e32 v43, 0
	s_addc_u32 s13, s13, s15
	v_lshlrev_b32_e32 v42, 2, v52
	v_lshl_add_u64 v[12:13], s[12:13], 0, v[42:43]
	v_mad_u64_u32 v[2:3], s[12:13], s10, v10, 0
	v_mov_b32_e32 v4, v3
	v_mad_u64_u32 v[4:5], s[12:13], s11, v10, v[4:5]
	v_add_u32_e32 v7, 2, v10
	v_mov_b32_e32 v3, v4
	v_mad_u64_u32 v[4:5], s[12:13], s10, v7, 0
	v_mov_b32_e32 v6, v5
	v_mad_u64_u32 v[6:7], s[12:13], s11, v7, v[6:7]
	v_add_u32_e32 v9, 4, v10
	v_mov_b32_e32 v5, v6
	v_mad_u64_u32 v[6:7], s[12:13], s10, v9, 0
	v_mov_b32_e32 v8, v7
	v_mad_u64_u32 v[8:9], s[12:13], s11, v9, v[8:9]
	v_add_u32_e32 v11, 6, v10
	v_mov_b32_e32 v7, v8
	v_mad_u64_u32 v[8:9], s[12:13], s10, v11, 0
	v_mov_b32_e32 v14, v9
	v_mad_u64_u32 v[14:15], s[12:13], s11, v11, v[14:15]
	v_add_u32_e32 v11, 8, v10
	v_mov_b32_e32 v9, v14
	v_mad_u64_u32 v[14:15], s[12:13], s10, v11, 0
	v_mov_b32_e32 v16, v15
	v_mad_u64_u32 v[16:17], s[12:13], s11, v11, v[16:17]
	v_add_u32_e32 v11, 10, v10
	v_mov_b32_e32 v15, v16
	v_mad_u64_u32 v[16:17], s[12:13], s10, v11, 0
	v_mov_b32_e32 v18, v17
	v_mad_u64_u32 v[18:19], s[12:13], s11, v11, v[18:19]
	v_add_u32_e32 v11, 12, v10
	v_mov_b32_e32 v17, v18
	v_mad_u64_u32 v[18:19], s[12:13], s10, v11, 0
	v_mov_b32_e32 v20, v19
	v_mad_u64_u32 v[20:21], s[12:13], s11, v11, v[20:21]
	v_add_u32_e32 v11, 14, v10
	v_mov_b32_e32 v19, v20
	v_mad_u64_u32 v[20:21], s[12:13], s10, v11, 0
	v_mov_b32_e32 v22, v21
	v_mad_u64_u32 v[22:23], s[12:13], s11, v11, v[22:23]
	v_lshl_add_u64 v[2:3], v[2:3], 2, v[12:13]
	v_lshl_add_u64 v[4:5], v[4:5], 2, v[12:13]
	v_lshl_add_u64 v[6:7], v[6:7], 2, v[12:13]
	v_lshl_add_u64 v[8:9], v[8:9], 2, v[12:13]
	v_lshl_add_u64 v[14:15], v[14:15], 2, v[12:13]
	v_mov_b32_e32 v21, v22
	v_add_u32_e32 v11, 16, v10
	v_lshl_add_u64 v[16:17], v[16:17], 2, v[12:13]
	v_lshl_add_u64 v[18:19], v[18:19], 2, v[12:13]
	v_lshl_add_u64 v[20:21], v[20:21], 2, v[12:13]
	global_load_dword v2, v[2:3], off sc1 nt
	s_nop 0
	global_load_dword v3, v[4:5], off sc1 nt
	s_nop 0
	global_load_dword v4, v[6:7], off sc1 nt
	global_load_dword v5, v[8:9], off sc1 nt
	s_nop 0
	global_load_dword v6, v[14:15], off sc1 nt
	global_load_dword v7, v[16:17], off sc1 nt
	global_load_dword v8, v[18:19], off sc1 nt
	global_load_dword v9, v[20:21], off sc1 nt
	v_mad_u64_u32 v[14:15], s[12:13], s10, v11, 0
	v_mov_b32_e32 v16, v15
	v_mad_u64_u32 v[16:17], s[12:13], s11, v11, v[16:17]
	v_add_u32_e32 v11, 18, v10
	v_mov_b32_e32 v15, v16
	v_mad_u64_u32 v[16:17], s[12:13], s10, v11, 0
	v_mov_b32_e32 v18, v17
	v_mad_u64_u32 v[18:19], s[12:13], s11, v11, v[18:19]
	v_add_u32_e32 v11, 20, v10
	v_mov_b32_e32 v17, v18
	v_mad_u64_u32 v[18:19], s[12:13], s10, v11, 0
	v_mov_b32_e32 v20, v19
	v_mad_u64_u32 v[20:21], s[12:13], s11, v11, v[20:21]
	v_add_u32_e32 v11, 22, v10
	v_mov_b32_e32 v19, v20
	v_mad_u64_u32 v[20:21], s[12:13], s10, v11, 0
	v_mov_b32_e32 v22, v21
	v_mad_u64_u32 v[22:23], s[12:13], s11, v11, v[22:23]
	v_add_u32_e32 v11, 24, v10
	v_mov_b32_e32 v21, v22
	v_mad_u64_u32 v[22:23], s[12:13], s10, v11, 0
	v_mov_b32_e32 v24, v23
	v_mad_u64_u32 v[24:25], s[12:13], s11, v11, v[24:25]
	v_add_u32_e32 v11, 26, v10
	v_mov_b32_e32 v23, v24
	v_mad_u64_u32 v[24:25], s[12:13], s10, v11, 0
	v_mov_b32_e32 v26, v25
	v_mad_u64_u32 v[26:27], s[12:13], s11, v11, v[26:27]
	v_add_u32_e32 v11, 28, v10
	v_mov_b32_e32 v25, v26
	v_mad_u64_u32 v[26:27], s[12:13], s10, v11, 0
	v_mov_b32_e32 v28, v27
	v_mad_u64_u32 v[28:29], s[12:13], s11, v11, v[28:29]
	v_add_u32_e32 v11, 30, v10
	v_mov_b32_e32 v27, v28
	v_mad_u64_u32 v[28:29], s[12:13], s10, v11, 0
	v_mov_b32_e32 v30, v29
	v_mad_u64_u32 v[30:31], s[12:13], s11, v11, v[30:31]
	v_lshl_add_u64 v[14:15], v[14:15], 2, v[12:13]
	v_mov_b32_e32 v29, v30
	v_add_u32_e32 v11, 32, v10
	v_lshl_add_u64 v[16:17], v[16:17], 2, v[12:13]
	v_lshl_add_u64 v[18:19], v[18:19], 2, v[12:13]
	v_lshl_add_u64 v[20:21], v[20:21], 2, v[12:13]
	v_lshl_add_u64 v[22:23], v[22:23], 2, v[12:13]
	v_lshl_add_u64 v[24:25], v[24:25], 2, v[12:13]
	v_lshl_add_u64 v[26:27], v[26:27], 2, v[12:13]
	v_lshl_add_u64 v[28:29], v[28:29], 2, v[12:13]
	global_load_dword v44, v[14:15], off sc1 nt
	global_load_dword v45, v[16:17], off sc1 nt
	global_load_dword v46, v[18:19], off sc1 nt
	global_load_dword v47, v[20:21], off sc1 nt
	global_load_dword v48, v[22:23], off sc1 nt
	global_load_dword v49, v[24:25], off sc1 nt
	global_load_dword v50, v[26:27], off sc1 nt
	global_load_dword v51, v[28:29], off sc1 nt
	v_mad_u64_u32 v[14:15], s[12:13], s10, v11, 0
	v_mov_b32_e32 v16, v15
	v_mad_u64_u32 v[16:17], s[12:13], s11, v11, v[16:17]
	v_add_u32_e32 v11, 34, v10
	v_mov_b32_e32 v15, v16
	v_mad_u64_u32 v[16:17], s[12:13], s10, v11, 0
	v_mov_b32_e32 v18, v17
	v_mad_u64_u32 v[18:19], s[12:13], s11, v11, v[18:19]
	v_add_u32_e32 v11, 36, v10
	v_mov_b32_e32 v17, v18
	v_mad_u64_u32 v[18:19], s[12:13], s10, v11, 0
	v_mov_b32_e32 v20, v19
	v_mad_u64_u32 v[20:21], s[12:13], s11, v11, v[20:21]
	v_add_u32_e32 v11, 38, v10
	v_mov_b32_e32 v19, v20
	v_mad_u64_u32 v[20:21], s[12:13], s10, v11, 0
	v_mov_b32_e32 v22, v21
	v_mad_u64_u32 v[22:23], s[12:13], s11, v11, v[22:23]
	v_add_u32_e32 v11, 40, v10
	v_mov_b32_e32 v21, v22
	v_mad_u64_u32 v[22:23], s[12:13], s10, v11, 0
	v_mov_b32_e32 v24, v23
	v_mad_u64_u32 v[24:25], s[12:13], s11, v11, v[24:25]
	v_add_u32_e32 v11, 42, v10
	v_mov_b32_e32 v23, v24
	v_mad_u64_u32 v[24:25], s[12:13], s10, v11, 0
	v_mov_b32_e32 v26, v25
	v_mad_u64_u32 v[26:27], s[12:13], s11, v11, v[26:27]
	v_add_u32_e32 v11, 44, v10
	v_mov_b32_e32 v25, v26
	v_mad_u64_u32 v[26:27], s[12:13], s10, v11, 0
	v_mov_b32_e32 v28, v27
	v_mad_u64_u32 v[28:29], s[12:13], s11, v11, v[28:29]
	v_add_u32_e32 v11, 46, v10
	v_mov_b32_e32 v27, v28
	v_mad_u64_u32 v[28:29], s[12:13], s10, v11, 0
	v_mov_b32_e32 v30, v29
	v_mad_u64_u32 v[30:31], s[12:13], s11, v11, v[30:31]
	v_lshl_add_u64 v[14:15], v[14:15], 2, v[12:13]
	v_mov_b32_e32 v29, v30
	v_add_u32_e32 v11, 48, v10
	v_lshl_add_u64 v[16:17], v[16:17], 2, v[12:13]
	v_lshl_add_u64 v[18:19], v[18:19], 2, v[12:13]
	v_lshl_add_u64 v[20:21], v[20:21], 2, v[12:13]
	v_lshl_add_u64 v[22:23], v[22:23], 2, v[12:13]
	v_lshl_add_u64 v[24:25], v[24:25], 2, v[12:13]
	v_lshl_add_u64 v[26:27], v[26:27], 2, v[12:13]
	v_lshl_add_u64 v[28:29], v[28:29], 2, v[12:13]
	global_load_dword v56, v[14:15], off sc1 nt
	global_load_dword v57, v[16:17], off sc1 nt
	global_load_dword v58, v[18:19], off sc1 nt
	global_load_dword v59, v[20:21], off sc1 nt
	global_load_dword v60, v[22:23], off sc1 nt
	global_load_dword v61, v[24:25], off sc1 nt
	global_load_dword v94, v[26:27], off sc1 nt
	global_load_dword v95, v[28:29], off sc1 nt
	v_mad_u64_u32 v[14:15], s[12:13], s10, v11, 0
	v_mov_b32_e32 v16, v15
	v_mad_u64_u32 v[16:17], s[12:13], s11, v11, v[16:17]
	v_add_u32_e32 v11, 50, v10
	v_mov_b32_e32 v15, v16
	v_mad_u64_u32 v[16:17], s[12:13], s10, v11, 0
	v_mov_b32_e32 v18, v17
	v_mad_u64_u32 v[18:19], s[12:13], s11, v11, v[18:19]
	v_add_u32_e32 v11, 52, v10
	v_mov_b32_e32 v17, v18
	v_mad_u64_u32 v[18:19], s[12:13], s10, v11, 0
	v_mov_b32_e32 v20, v19
	v_mad_u64_u32 v[20:21], s[12:13], s11, v11, v[20:21]
	v_add_u32_e32 v11, 54, v10
	v_mov_b32_e32 v19, v20
	v_mad_u64_u32 v[20:21], s[12:13], s10, v11, 0
	v_mov_b32_e32 v22, v21
	v_mad_u64_u32 v[22:23], s[12:13], s11, v11, v[22:23]
	v_add_u32_e32 v11, 56, v10
	v_mov_b32_e32 v21, v22
	v_mad_u64_u32 v[22:23], s[12:13], s10, v11, 0
	v_mov_b32_e32 v24, v23
	v_mad_u64_u32 v[24:25], s[12:13], s11, v11, v[24:25]
	v_add_u32_e32 v11, 58, v10
	v_mov_b32_e32 v23, v24
	v_mad_u64_u32 v[24:25], s[12:13], s10, v11, 0
	v_mov_b32_e32 v26, v25
	v_mad_u64_u32 v[26:27], s[12:13], s11, v11, v[26:27]
	v_add_u32_e32 v11, 60, v10
	v_mov_b32_e32 v25, v26
	v_mad_u64_u32 v[26:27], s[12:13], s10, v11, 0
	v_mov_b32_e32 v28, v27
	v_mad_u64_u32 v[28:29], s[12:13], s11, v11, v[28:29]
	v_add_u32_e32 v11, 62, v10
	v_mov_b32_e32 v27, v28
	v_mad_u64_u32 v[28:29], s[12:13], s10, v11, 0
	v_mov_b32_e32 v30, v29
	v_mad_u64_u32 v[30:31], s[10:11], s11, v11, v[30:31]
	v_lshl_add_u64 v[14:15], v[14:15], 2, v[12:13]
	v_mov_b32_e32 v29, v30
	v_lshl_add_u64 v[16:17], v[16:17], 2, v[12:13]
	v_lshl_add_u64 v[18:19], v[18:19], 2, v[12:13]
	v_lshl_add_u64 v[20:21], v[20:21], 2, v[12:13]
	v_lshl_add_u64 v[22:23], v[22:23], 2, v[12:13]
	v_lshl_add_u64 v[24:25], v[24:25], 2, v[12:13]
	v_lshl_add_u64 v[26:27], v[26:27], 2, v[12:13]
	v_lshl_add_u64 v[12:13], v[28:29], 2, v[12:13]
	global_load_dword v96, v[14:15], off sc1 nt
	global_load_dword v97, v[16:17], off sc1 nt
	global_load_dword v98, v[18:19], off sc1 nt
	global_load_dword v99, v[20:21], off sc1 nt
	global_load_dword v100, v[22:23], off sc1 nt
	global_load_dword v101, v[24:25], off sc1 nt
	global_load_dword v102, v[26:27], off sc1 nt
	global_load_dword v103, v[12:13], off sc1 nt
	s_cmp_eq_u64 s[8:9], 0
	s_mov_b64 s[16:17], 0
	s_cbranch_scc1 .LBB0_270
	v_mov_b32_e32 v11, v43
	v_lshl_add_u64 v[54:55], v[10:11], 2, s[8:9]
	global_load_dword v10, v[54:55], off sc1 nt
	global_load_dword v11, v[54:55], off offset:8 sc1 nt
	global_load_dword v12, v[54:55], off offset:16 sc1 nt
	global_load_dword v13, v[54:55], off offset:24 sc1 nt
	global_load_dword v14, v[54:55], off offset:32 sc1 nt
	global_load_dword v15, v[54:55], off offset:40 sc1 nt
	global_load_dword v16, v[54:55], off offset:48 sc1 nt
	global_load_dword v17, v[54:55], off offset:56 sc1 nt
	global_load_dword v18, v[54:55], off offset:64 sc1 nt
	global_load_dword v19, v[54:55], off offset:72 sc1 nt
	global_load_dword v20, v[54:55], off offset:80 sc1 nt
	global_load_dword v21, v[54:55], off offset:88 sc1 nt
	global_load_dword v22, v[54:55], off offset:96 sc1 nt
	global_load_dword v23, v[54:55], off offset:104 sc1 nt
	global_load_dword v24, v[54:55], off offset:112 sc1 nt
	global_load_dword v25, v[54:55], off offset:120 sc1 nt
	global_load_dword v26, v[54:55], off offset:128 sc1 nt
	global_load_dword v27, v[54:55], off offset:136 sc1 nt
	global_load_dword v28, v[54:55], off offset:144 sc1 nt
	global_load_dword v29, v[54:55], off offset:152 sc1 nt
	global_load_dword v30, v[54:55], off offset:160 sc1 nt
	global_load_dword v31, v[54:55], off offset:168 sc1 nt
	global_load_dword v32, v[54:55], off offset:176 sc1 nt
	global_load_dword v33, v[54:55], off offset:184 sc1 nt
	global_load_dword v34, v[54:55], off offset:192 sc1 nt
	global_load_dword v35, v[54:55], off offset:200 sc1 nt
	global_load_dword v36, v[54:55], off offset:208 sc1 nt
	global_load_dword v37, v[54:55], off offset:216 sc1 nt
	global_load_dword v38, v[54:55], off offset:224 sc1 nt
	global_load_dword v39, v[54:55], off offset:232 sc1 nt
	global_load_dword v40, v[54:55], off offset:240 sc1 nt
	global_load_dword v41, v[54:55], off offset:248 sc1 nt
	s_mov_b64 s[16:17], s[8:9]
	s_branch .LBB0_271

.LBB0_283:
	s_ashr_i32 s11, s10, 31
	s_lshl_b64 s[36:37], s[10:11], 2
	v_add_u32_e32 v136, s8, v1
	s_add_u32 s34, s34, s36
	s_addc_u32 s35, s35, s37
	v_ashrrev_i32_e32 v137, 31, v136
	v_lshl_add_u64 v[128:129], v[42:43], 2, s[34:35]
	v_mul_lo_u32 v54, s20, v137
	v_mul_lo_u32 v106, s21, v136
	v_mad_u64_u32 v[104:105], s[34:35], s20, v136, 0
	v_add3_u32 v105, v105, v54, v106
	v_add_u32_e32 v54, 2, v136
	v_ashrrev_i32_e32 v106, 31, v54
	v_mul_lo_u32 v108, s20, v106
	v_mul_lo_u32 v109, s21, v54
	v_mad_u64_u32 v[106:107], s[34:35], s20, v54, 0
	v_add_u32_e32 v54, 4, v136
	v_add3_u32 v107, v107, v108, v109
	v_ashrrev_i32_e32 v108, 31, v54
	v_mul_lo_u32 v110, s20, v108
	v_mul_lo_u32 v111, s21, v54
	v_mad_u64_u32 v[108:109], s[34:35], s20, v54, 0
	v_add_u32_e32 v54, 6, v136
	v_add3_u32 v109, v109, v110, v111
	v_ashrrev_i32_e32 v110, 31, v54
	v_mul_lo_u32 v112, s20, v110
	v_mul_lo_u32 v113, s21, v54
	v_mad_u64_u32 v[110:111], s[34:35], s20, v54, 0
	v_add_u32_e32 v54, 8, v136
	v_add3_u32 v111, v111, v112, v113
	v_ashrrev_i32_e32 v112, 31, v54
	v_mul_lo_u32 v114, s20, v112
	v_mul_lo_u32 v115, s21, v54
	v_mad_u64_u32 v[112:113], s[34:35], s20, v54, 0
	v_add_u32_e32 v54, 10, v136
	v_add3_u32 v113, v113, v114, v115
	v_ashrrev_i32_e32 v114, 31, v54
	v_mul_lo_u32 v116, s20, v114
	v_mul_lo_u32 v117, s21, v54
	v_mad_u64_u32 v[114:115], s[34:35], s20, v54, 0
	v_add_u32_e32 v54, 12, v136
	v_add3_u32 v115, v115, v116, v117
	v_ashrrev_i32_e32 v116, 31, v54
	v_mul_lo_u32 v118, s20, v116
	v_mul_lo_u32 v119, s21, v54
	v_mad_u64_u32 v[116:117], s[34:35], s20, v54, 0
	v_add_u32_e32 v54, 14, v136
	v_add3_u32 v117, v117, v118, v119
	v_ashrrev_i32_e32 v118, 31, v54
	v_mul_lo_u32 v120, s20, v118
	v_mul_lo_u32 v121, s21, v54
	v_mad_u64_u32 v[118:119], s[34:35], s20, v54, 0
	v_lshl_add_u64 v[104:105], v[104:105], 2, v[128:129]
	v_lshl_add_u64 v[106:107], v[106:107], 2, v[128:129]
	v_lshl_add_u64 v[108:109], v[108:109], 2, v[128:129]
	v_lshl_add_u64 v[110:111], v[110:111], 2, v[128:129]
	v_lshl_add_u64 v[112:113], v[112:113], 2, v[128:129]
	v_add3_u32 v119, v119, v120, v121
	v_add_u32_e32 v54, 16, v136
	v_lshl_add_u64 v[114:115], v[114:115], 2, v[128:129]
	v_lshl_add_u64 v[116:117], v[116:117], 2, v[128:129]
	v_lshl_add_u64 v[118:119], v[118:119], 2, v[128:129]
	global_load_dword v105, v[104:105], off sc1 nt
	s_nop 0
	global_load_dword v104, v[106:107], off sc1 nt
	s_nop 0
	global_load_dword v107, v[108:109], off sc1 nt
	global_load_dword v106, v[110:111], off sc1 nt
	s_nop 0
	global_load_dword v109, v[112:113], off sc1 nt
	global_load_dword v108, v[114:115], off sc1 nt
	global_load_dword v111, v[116:117], off sc1 nt
	global_load_dword v110, v[118:119], off sc1 nt
	v_ashrrev_i32_e32 v112, 31, v54
	v_mul_lo_u32 v114, s20, v112
	v_mul_lo_u32 v115, s21, v54
	v_mad_u64_u32 v[112:113], s[34:35], s20, v54, 0
	v_add_u32_e32 v54, 18, v136
	v_add3_u32 v113, v113, v114, v115
	v_ashrrev_i32_e32 v114, 31, v54
	v_mul_lo_u32 v116, s20, v114
	v_mul_lo_u32 v117, s21, v54
	v_mad_u64_u32 v[114:115], s[34:35], s20, v54, 0
	v_add_u32_e32 v54, 20, v136
	v_add3_u32 v115, v115, v116, v117
	v_ashrrev_i32_e32 v116, 31, v54
	v_mul_lo_u32 v118, s20, v116
	v_mul_lo_u32 v119, s21, v54
	v_mad_u64_u32 v[116:117], s[34:35], s20, v54, 0
	v_add_u32_e32 v54, 22, v136
	v_add3_u32 v117, v117, v118, v119
	v_ashrrev_i32_e32 v118, 31, v54
	v_mul_lo_u32 v120, s20, v118
	v_mul_lo_u32 v121, s21, v54
	v_mad_u64_u32 v[118:119], s[34:35], s20, v54, 0
	v_add_u32_e32 v54, 24, v136
	v_add3_u32 v119, v119, v120, v121
	v_ashrrev_i32_e32 v120, 31, v54
	v_mul_lo_u32 v122, s20, v120
	v_mul_lo_u32 v123, s21, v54
	v_mad_u64_u32 v[120:121], s[34:35], s20, v54, 0
	v_add_u32_e32 v54, 26, v136
	v_add3_u32 v121, v121, v122, v123
	v_ashrrev_i32_e32 v122, 31, v54
	v_mul_lo_u32 v124, s20, v122
	v_mul_lo_u32 v125, s21, v54
	v_mad_u64_u32 v[122:123], s[34:35], s20, v54, 0
	v_add_u32_e32 v54, 28, v136
	v_add3_u32 v123, v123, v124, v125
	v_ashrrev_i32_e32 v124, 31, v54
	v_mul_lo_u32 v126, s20, v124
	v_mul_lo_u32 v127, s21, v54
	v_mad_u64_u32 v[124:125], s[34:35], s20, v54, 0
	v_add_u32_e32 v54, 30, v136
	v_add3_u32 v125, v125, v126, v127
	v_ashrrev_i32_e32 v126, 31, v54
	v_mul_lo_u32 v130, s20, v126
	v_mul_lo_u32 v131, s21, v54
	v_mad_u64_u32 v[126:127], s[34:35], s20, v54, 0
	v_lshl_add_u64 v[112:113], v[112:113], 2, v[128:129]
	v_lshl_add_u64 v[114:115], v[114:115], 2, v[128:129]
	v_lshl_add_u64 v[116:117], v[116:117], 2, v[128:129]
	v_lshl_add_u64 v[118:119], v[118:119], 2, v[128:129]
	v_lshl_add_u64 v[120:121], v[120:121], 2, v[128:129]
	v_add3_u32 v127, v127, v130, v131
	v_add_u32_e32 v54, 32, v136
	v_lshl_add_u64 v[122:123], v[122:123], 2, v[128:129]
	v_lshl_add_u64 v[124:125], v[124:125], 2, v[128:129]
	v_lshl_add_u64 v[126:127], v[126:127], 2, v[128:129]
	global_load_dword v113, v[112:113], off sc1 nt
	s_nop 0
	global_load_dword v112, v[114:115], off sc1 nt
	s_nop 0
	global_load_dword v115, v[116:117], off sc1 nt
	global_load_dword v114, v[118:119], off sc1 nt
	s_nop 0
	global_load_dword v117, v[120:121], off sc1 nt
	global_load_dword v116, v[122:123], off sc1 nt
	global_load_dword v119, v[124:125], off sc1 nt
	global_load_dword v118, v[126:127], off sc1 nt
	v_ashrrev_i32_e32 v120, 31, v54
	v_mul_lo_u32 v122, s20, v120
	v_mul_lo_u32 v123, s21, v54
	v_mad_u64_u32 v[120:121], s[34:35], s20, v54, 0
	v_add_u32_e32 v54, 34, v136
	v_add3_u32 v121, v121, v122, v123
	v_ashrrev_i32_e32 v122, 31, v54
	v_mul_lo_u32 v124, s20, v122
	v_mul_lo_u32 v125, s21, v54
	v_mad_u64_u32 v[122:123], s[34:35], s20, v54, 0
	v_add_u32_e32 v54, 36, v136
	v_add3_u32 v123, v123, v124, v125
	v_ashrrev_i32_e32 v124, 31, v54
	v_mul_lo_u32 v126, s20, v124
	v_mul_lo_u32 v127, s21, v54
	v_mad_u64_u32 v[124:125], s[34:35], s20, v54, 0
	v_add_u32_e32 v54, 38, v136
	v_add3_u32 v125, v125, v126, v127
	v_ashrrev_i32_e32 v126, 31, v54
	v_mul_lo_u32 v130, s20, v126
	v_mul_lo_u32 v131, s21, v54
	v_mad_u64_u32 v[126:127], s[34:35], s20, v54, 0
	v_add_u32_e32 v54, 40, v136
	v_add3_u32 v127, v127, v130, v131
	v_ashrrev_i32_e32 v130, 31, v54
	v_mul_lo_u32 v132, s20, v130
	v_mul_lo_u32 v133, s21, v54
	v_mad_u64_u32 v[130:131], s[34:35], s20, v54, 0
	v_add_u32_e32 v54, 42, v136
	v_add3_u32 v131, v131, v132, v133
	v_ashrrev_i32_e32 v132, 31, v54
	v_mul_lo_u32 v134, s20, v132
	v_mul_lo_u32 v135, s21, v54
	v_mad_u64_u32 v[132:133], s[34:35], s20, v54, 0
	v_add_u32_e32 v54, 44, v136
	v_add3_u32 v133, v133, v134, v135
	v_ashrrev_i32_e32 v134, 31, v54
	v_mul_lo_u32 v143, s20, v134
	v_mul_lo_u32 v144, s21, v54
	v_mad_u64_u32 v[134:135], s[34:35], s20, v54, 0
	v_add_u32_e32 v54, 46, v136
	v_add3_u32 v135, v135, v143, v144
	v_ashrrev_i32_e32 v143, 31, v54
	v_mul_lo_u32 v143, s20, v143
	v_mul_lo_u32 v146, s21, v54
	v_mad_u64_u32 v[144:145], s[34:35], s20, v54, 0
	v_lshl_add_u64 v[120:121], v[120:121], 2, v[128:129]
	v_lshl_add_u64 v[122:123], v[122:123], 2, v[128:129]
	v_lshl_add_u64 v[124:125], v[124:125], 2, v[128:129]
	v_lshl_add_u64 v[126:127], v[126:127], 2, v[128:129]
	v_lshl_add_u64 v[130:131], v[130:131], 2, v[128:129]
	v_add3_u32 v145, v145, v143, v146
	v_add_u32_e32 v54, 48, v136
	v_lshl_add_u64 v[132:133], v[132:133], 2, v[128:129]
	v_lshl_add_u64 v[134:135], v[134:135], 2, v[128:129]
	v_lshl_add_u64 v[144:145], v[144:145], 2, v[128:129]
	global_load_dword v121, v[120:121], off sc1 nt
	s_nop 0
	global_load_dword v120, v[122:123], off sc1 nt
	s_nop 0
	global_load_dword v123, v[124:125], off sc1 nt
	global_load_dword v122, v[126:127], off sc1 nt
	s_nop 0
	global_load_dword v125, v[130:131], off sc1 nt
	global_load_dword v124, v[132:133], off sc1 nt
	global_load_dword v127, v[134:135], off sc1 nt
	global_load_dword v126, v[144:145], off sc1 nt
	v_ashrrev_i32_e32 v130, 31, v54
	v_mul_lo_u32 v132, s20, v130
	v_mul_lo_u32 v133, s21, v54
	v_mad_u64_u32 v[130:131], s[34:35], s20, v54, 0
	v_add_u32_e32 v54, 50, v136
	v_add3_u32 v131, v131, v132, v133
	v_ashrrev_i32_e32 v132, 31, v54
	v_mul_lo_u32 v134, s20, v132
	v_mul_lo_u32 v135, s21, v54
	v_mad_u64_u32 v[132:133], s[34:35], s20, v54, 0
	v_add_u32_e32 v54, 52, v136
	v_add3_u32 v133, v133, v134, v135
	v_ashrrev_i32_e32 v134, 31, v54
	v_mul_lo_u32 v143, s20, v134
	v_mul_lo_u32 v144, s21, v54
	v_mad_u64_u32 v[134:135], s[34:35], s20, v54, 0
	v_add_u32_e32 v54, 54, v136
	v_add3_u32 v135, v135, v143, v144
	v_ashrrev_i32_e32 v143, 31, v54
	v_mul_lo_u32 v143, s20, v143
	v_mul_lo_u32 v146, s21, v54
	v_mad_u64_u32 v[144:145], s[34:35], s20, v54, 0
	v_add_u32_e32 v54, 56, v136
	v_add3_u32 v145, v145, v143, v146
	v_ashrrev_i32_e32 v143, 31, v54
	v_mul_lo_u32 v143, s20, v143
	v_mul_lo_u32 v148, s21, v54
	v_mad_u64_u32 v[146:147], s[34:35], s20, v54, 0
	v_add_u32_e32 v54, 58, v136
	v_add3_u32 v147, v147, v143, v148
	v_ashrrev_i32_e32 v143, 31, v54
	v_mul_lo_u32 v143, s20, v143
	v_mul_lo_u32 v150, s21, v54
	v_mad_u64_u32 v[148:149], s[34:35], s20, v54, 0
	v_add_u32_e32 v54, 60, v136
	v_add3_u32 v149, v149, v143, v150
	v_ashrrev_i32_e32 v143, 31, v54
	v_mul_lo_u32 v143, s20, v143
	v_mul_lo_u32 v152, s21, v54
	v_mad_u64_u32 v[150:151], s[34:35], s20, v54, 0
	v_add_u32_e32 v54, 62, v136
	v_add3_u32 v151, v151, v143, v152
	v_ashrrev_i32_e32 v143, 31, v54
	v_mul_lo_u32 v143, s20, v143
	v_mul_lo_u32 v154, s21, v54
	v_mad_u64_u32 v[152:153], s[20:21], s20, v54, 0
	v_lshl_add_u64 v[130:131], v[130:131], 2, v[128:129]
	v_lshl_add_u64 v[132:133], v[132:133], 2, v[128:129]
	v_lshl_add_u64 v[134:135], v[134:135], 2, v[128:129]
	v_add3_u32 v153, v153, v143, v154
	v_lshl_add_u64 v[144:145], v[144:145], 2, v[128:129]
	v_lshl_add_u64 v[146:147], v[146:147], 2, v[128:129]
	v_lshl_add_u64 v[148:149], v[148:149], 2, v[128:129]
	v_lshl_add_u64 v[150:151], v[150:151], 2, v[128:129]
	v_lshl_add_u64 v[152:153], v[152:153], 2, v[128:129]
	global_load_dword v129, v[130:131], off sc1 nt
	global_load_dword v128, v[132:133], off sc1 nt
	s_nop 0
	global_load_dword v131, v[134:135], off sc1 nt
	global_load_dword v130, v[144:145], off sc1 nt
	global_load_dword v133, v[146:147], off sc1 nt
	global_load_dword v132, v[148:149], off sc1 nt
	s_nop 0
	global_load_dword v135, v[150:151], off sc1 nt
	global_load_dword v134, v[152:153], off sc1 nt
	s_cmp_eq_u64 s[22:23], 0
	s_mov_b64 s[20:21], 0
	s_cbranch_scc1 .LBB0_285
	v_lshl_add_u64 v[136:137], v[136:137], 2, s[22:23]
	global_load_dword v63, v[136:137], off sc1 nt
	global_load_dword v62, v[136:137], off offset:8 sc1 nt
	global_load_dword v65, v[136:137], off offset:16 sc1 nt
	global_load_dword v64, v[136:137], off offset:24 sc1 nt
	global_load_dword v67, v[136:137], off offset:32 sc1 nt
	global_load_dword v66, v[136:137], off offset:40 sc1 nt
	global_load_dword v69, v[136:137], off offset:48 sc1 nt
	global_load_dword v68, v[136:137], off offset:56 sc1 nt
	global_load_dword v71, v[136:137], off offset:64 sc1 nt
	global_load_dword v70, v[136:137], off offset:72 sc1 nt
	global_load_dword v73, v[136:137], off offset:80 sc1 nt
	global_load_dword v72, v[136:137], off offset:88 sc1 nt
	global_load_dword v75, v[136:137], off offset:96 sc1 nt
	global_load_dword v74, v[136:137], off offset:104 sc1 nt
	global_load_dword v77, v[136:137], off offset:112 sc1 nt
	global_load_dword v76, v[136:137], off offset:120 sc1 nt
	global_load_dword v79, v[136:137], off offset:128 sc1 nt
	global_load_dword v78, v[136:137], off offset:136 sc1 nt
	global_load_dword v81, v[136:137], off offset:144 sc1 nt
	global_load_dword v80, v[136:137], off offset:152 sc1 nt
	global_load_dword v83, v[136:137], off offset:160 sc1 nt
	global_load_dword v82, v[136:137], off offset:168 sc1 nt
	global_load_dword v85, v[136:137], off offset:176 sc1 nt
	global_load_dword v84, v[136:137], off offset:184 sc1 nt
	global_load_dword v87, v[136:137], off offset:192 sc1 nt
	global_load_dword v86, v[136:137], off offset:200 sc1 nt
	global_load_dword v89, v[136:137], off offset:208 sc1 nt
	global_load_dword v88, v[136:137], off offset:216 sc1 nt
	global_load_dword v91, v[136:137], off offset:224 sc1 nt
	global_load_dword v90, v[136:137], off offset:232 sc1 nt
	global_load_dword v93, v[136:137], off offset:240 sc1 nt
	global_load_dword v92, v[136:137], off offset:248 sc1 nt
	s_mov_b64 s[20:21], s[22:23]

.LBB0_297:
	s_ashr_i32 s5, s4, 31
	s_lshl_b64 s[36:37], s[4:5], 2
	v_add_u32_e32 v136, s2, v1
	s_add_u32 s34, s34, s36
	s_addc_u32 s35, s35, s37
	v_ashrrev_i32_e32 v137, 31, v136
	v_lshl_add_u64 v[96:97], v[42:43], 2, s[34:35]
	v_mul_lo_u32 v4, s16, v137
	v_mul_lo_u32 v5, s17, v136
	v_mad_u64_u32 v[2:3], s[34:35], s16, v136, 0
	v_add3_u32 v3, v3, v4, v5
	v_add_u32_e32 v4, 2, v136
	v_ashrrev_i32_e32 v5, 31, v4
	v_mul_lo_u32 v6, s16, v5
	v_mul_lo_u32 v7, s17, v4
	v_mad_u64_u32 v[4:5], s[34:35], s16, v4, 0
	v_add3_u32 v5, v5, v6, v7
	v_add_u32_e32 v6, 4, v136
	v_ashrrev_i32_e32 v7, 31, v6
	v_mul_lo_u32 v8, s16, v7
	v_mul_lo_u32 v9, s17, v6
	v_mad_u64_u32 v[6:7], s[34:35], s16, v6, 0
	v_add3_u32 v7, v7, v8, v9
	v_add_u32_e32 v8, 6, v136
	v_ashrrev_i32_e32 v9, 31, v8
	v_mul_lo_u32 v44, s16, v9
	v_mul_lo_u32 v45, s17, v8
	v_mad_u64_u32 v[8:9], s[34:35], s16, v8, 0
	v_add3_u32 v9, v9, v44, v45
	v_add_u32_e32 v44, 8, v136
	v_ashrrev_i32_e32 v45, 31, v44
	v_mul_lo_u32 v46, s16, v45
	v_mul_lo_u32 v47, s17, v44
	v_mad_u64_u32 v[44:45], s[34:35], s16, v44, 0
	v_add3_u32 v45, v45, v46, v47
	v_add_u32_e32 v46, 10, v136
	v_ashrrev_i32_e32 v47, 31, v46
	v_mul_lo_u32 v48, s16, v47
	v_mul_lo_u32 v49, s17, v46
	v_mad_u64_u32 v[46:47], s[34:35], s16, v46, 0
	v_add3_u32 v47, v47, v48, v49
	v_add_u32_e32 v48, 12, v136
	v_ashrrev_i32_e32 v49, 31, v48
	v_mul_lo_u32 v50, s16, v49
	v_mul_lo_u32 v51, s17, v48
	v_mad_u64_u32 v[48:49], s[34:35], s16, v48, 0
	v_add3_u32 v49, v49, v50, v51
	v_add_u32_e32 v50, 14, v136
	v_ashrrev_i32_e32 v51, 31, v50
	v_mul_lo_u32 v56, s16, v51
	v_mul_lo_u32 v57, s17, v50
	v_mad_u64_u32 v[50:51], s[34:35], s16, v50, 0
	v_lshl_add_u64 v[2:3], v[2:3], 2, v[96:97]
	v_lshl_add_u64 v[4:5], v[4:5], 2, v[96:97]
	v_lshl_add_u64 v[6:7], v[6:7], 2, v[96:97]
	v_lshl_add_u64 v[8:9], v[8:9], 2, v[96:97]
	v_lshl_add_u64 v[44:45], v[44:45], 2, v[96:97]
	v_add3_u32 v51, v51, v56, v57
	v_lshl_add_u64 v[46:47], v[46:47], 2, v[96:97]
	v_lshl_add_u64 v[48:49], v[48:49], 2, v[96:97]
	v_lshl_add_u64 v[50:51], v[50:51], 2, v[96:97]
	global_load_dword v2, v[2:3], off sc1 nt
	s_nop 0
	global_load_dword v3, v[4:5], off sc1 nt
	s_nop 0
	global_load_dword v4, v[6:7], off sc1 nt
	global_load_dword v5, v[8:9], off sc1 nt
	s_nop 0
	global_load_dword v6, v[44:45], off sc1 nt
	global_load_dword v7, v[46:47], off sc1 nt
	global_load_dword v8, v[48:49], off sc1 nt
	global_load_dword v9, v[50:51], off sc1 nt
	v_add_u32_e32 v44, 16, v136
	v_ashrrev_i32_e32 v45, 31, v44
	v_mul_lo_u32 v46, s16, v45
	v_mul_lo_u32 v47, s17, v44
	v_mad_u64_u32 v[44:45], s[34:35], s16, v44, 0
	v_add3_u32 v45, v45, v46, v47
	v_add_u32_e32 v46, 18, v136
	v_ashrrev_i32_e32 v47, 31, v46
	v_mul_lo_u32 v48, s16, v47
	v_mul_lo_u32 v49, s17, v46
	v_mad_u64_u32 v[46:47], s[34:35], s16, v46, 0
	v_add3_u32 v47, v47, v48, v49
	v_add_u32_e32 v48, 20, v136
	v_ashrrev_i32_e32 v49, 31, v48
	v_mul_lo_u32 v50, s16, v49
	v_mul_lo_u32 v51, s17, v48
	v_mad_u64_u32 v[48:49], s[34:35], s16, v48, 0
	v_add3_u32 v49, v49, v50, v51
	v_add_u32_e32 v50, 22, v136
	v_ashrrev_i32_e32 v51, 31, v50
	v_mul_lo_u32 v56, s16, v51
	v_mul_lo_u32 v57, s17, v50
	v_mad_u64_u32 v[50:51], s[34:35], s16, v50, 0
	v_add3_u32 v51, v51, v56, v57
	v_add_u32_e32 v56, 24, v136
	v_ashrrev_i32_e32 v57, 31, v56
	v_mul_lo_u32 v58, s16, v57
	v_mul_lo_u32 v59, s17, v56
	v_mad_u64_u32 v[56:57], s[34:35], s16, v56, 0
	v_add3_u32 v57, v57, v58, v59
	v_add_u32_e32 v58, 26, v136
	v_ashrrev_i32_e32 v59, 31, v58
	v_mul_lo_u32 v60, s16, v59
	v_mul_lo_u32 v61, s17, v58
	v_mad_u64_u32 v[58:59], s[34:35], s16, v58, 0
	v_add3_u32 v59, v59, v60, v61
	v_add_u32_e32 v60, 28, v136
	v_ashrrev_i32_e32 v61, 31, v60
	v_mul_lo_u32 v94, s16, v61
	v_mul_lo_u32 v95, s17, v60
	v_mad_u64_u32 v[60:61], s[34:35], s16, v60, 0
	v_add3_u32 v61, v61, v94, v95
	v_add_u32_e32 v94, 30, v136
	v_ashrrev_i32_e32 v95, 31, v94
	v_mul_lo_u32 v98, s16, v95
	v_mul_lo_u32 v99, s17, v94
	v_mad_u64_u32 v[94:95], s[34:35], s16, v94, 0
	v_lshl_add_u64 v[44:45], v[44:45], 2, v[96:97]
	v_lshl_add_u64 v[46:47], v[46:47], 2, v[96:97]
	v_lshl_add_u64 v[48:49], v[48:49], 2, v[96:97]
	v_lshl_add_u64 v[50:51], v[50:51], 2, v[96:97]
	v_lshl_add_u64 v[56:57], v[56:57], 2, v[96:97]
	v_add3_u32 v95, v95, v98, v99
	v_lshl_add_u64 v[58:59], v[58:59], 2, v[96:97]
	v_lshl_add_u64 v[60:61], v[60:61], 2, v[96:97]
	v_lshl_add_u64 v[94:95], v[94:95], 2, v[96:97]
	global_load_dword v44, v[44:45], off sc1 nt
	s_nop 0
	global_load_dword v45, v[46:47], off sc1 nt
	s_nop 0
	global_load_dword v46, v[48:49], off sc1 nt
	global_load_dword v47, v[50:51], off sc1 nt
	s_nop 0
	global_load_dword v48, v[56:57], off sc1 nt
	global_load_dword v49, v[58:59], off sc1 nt
	global_load_dword v50, v[60:61], off sc1 nt
	global_load_dword v51, v[94:95], off sc1 nt
	v_add_u32_e32 v56, 32, v136
	v_ashrrev_i32_e32 v57, 31, v56
	v_mul_lo_u32 v58, s16, v57
	v_mul_lo_u32 v59, s17, v56
	v_mad_u64_u32 v[56:57], s[34:35], s16, v56, 0
	v_add3_u32 v57, v57, v58, v59
	v_add_u32_e32 v58, 34, v136
	v_ashrrev_i32_e32 v59, 31, v58
	v_mul_lo_u32 v60, s16, v59
	v_mul_lo_u32 v61, s17, v58
	v_mad_u64_u32 v[58:59], s[34:35], s16, v58, 0
	v_add3_u32 v59, v59, v60, v61
	v_add_u32_e32 v60, 36, v136
	v_ashrrev_i32_e32 v61, 31, v60
	v_mul_lo_u32 v94, s16, v61
	v_mul_lo_u32 v95, s17, v60
	v_mad_u64_u32 v[60:61], s[34:35], s16, v60, 0
	v_add3_u32 v61, v61, v94, v95
	v_add_u32_e32 v94, 38, v136
	v_ashrrev_i32_e32 v95, 31, v94
	v_mul_lo_u32 v98, s16, v95
	v_mul_lo_u32 v99, s17, v94
	v_mad_u64_u32 v[94:95], s[34:35], s16, v94, 0
	v_add3_u32 v95, v95, v98, v99
	v_add_u32_e32 v98, 40, v136
	v_ashrrev_i32_e32 v99, 31, v98
	v_mul_lo_u32 v100, s16, v99
	v_mul_lo_u32 v101, s17, v98
	v_mad_u64_u32 v[98:99], s[34:35], s16, v98, 0
	v_add3_u32 v99, v99, v100, v101
	v_add_u32_e32 v100, 42, v136
	v_ashrrev_i32_e32 v101, 31, v100
	v_mul_lo_u32 v102, s16, v101
	v_mul_lo_u32 v103, s17, v100
	v_mad_u64_u32 v[100:101], s[34:35], s16, v100, 0
	v_add3_u32 v101, v101, v102, v103
	v_add_u32_e32 v102, 44, v136
	v_ashrrev_i32_e32 v103, 31, v102
	v_mul_lo_u32 v150, s16, v103
	v_mul_lo_u32 v151, s17, v102
	v_mad_u64_u32 v[102:103], s[34:35], s16, v102, 0
	v_add3_u32 v103, v103, v150, v151
	v_add_u32_e32 v150, 46, v136
	v_ashrrev_i32_e32 v151, 31, v150
	v_mul_lo_u32 v152, s16, v151
	v_mul_lo_u32 v153, s17, v150
	v_mad_u64_u32 v[150:151], s[34:35], s16, v150, 0
	v_lshl_add_u64 v[56:57], v[56:57], 2, v[96:97]
	v_lshl_add_u64 v[58:59], v[58:59], 2, v[96:97]
	v_lshl_add_u64 v[60:61], v[60:61], 2, v[96:97]
	v_lshl_add_u64 v[94:95], v[94:95], 2, v[96:97]
	v_lshl_add_u64 v[98:99], v[98:99], 2, v[96:97]
	v_add3_u32 v151, v151, v152, v153
	v_lshl_add_u64 v[100:101], v[100:101], 2, v[96:97]
	v_lshl_add_u64 v[102:103], v[102:103], 2, v[96:97]
	v_lshl_add_u64 v[150:151], v[150:151], 2, v[96:97]
	global_load_dword v56, v[56:57], off sc1 nt
	s_nop 0
	global_load_dword v57, v[58:59], off sc1 nt
	s_nop 0
	global_load_dword v58, v[60:61], off sc1 nt
	global_load_dword v59, v[94:95], off sc1 nt
	s_nop 0
	global_load_dword v60, v[98:99], off sc1 nt
	global_load_dword v61, v[100:101], off sc1 nt
	global_load_dword v94, v[102:103], off sc1 nt
	global_load_dword v95, v[150:151], off sc1 nt
	v_add_u32_e32 v98, 48, v136
	v_ashrrev_i32_e32 v99, 31, v98
	v_mul_lo_u32 v100, s16, v99
	v_mul_lo_u32 v101, s17, v98
	v_mad_u64_u32 v[98:99], s[34:35], s16, v98, 0
	v_add3_u32 v99, v99, v100, v101
	v_add_u32_e32 v100, 50, v136
	v_ashrrev_i32_e32 v101, 31, v100
	v_mul_lo_u32 v102, s16, v101
	v_mul_lo_u32 v103, s17, v100
	v_mad_u64_u32 v[100:101], s[34:35], s16, v100, 0
	v_add3_u32 v101, v101, v102, v103
	v_add_u32_e32 v102, 52, v136
	v_ashrrev_i32_e32 v103, 31, v102
	v_mul_lo_u32 v150, s16, v103
	v_mul_lo_u32 v151, s17, v102
	v_mad_u64_u32 v[102:103], s[34:35], s16, v102, 0
	v_add3_u32 v103, v103, v150, v151
	v_add_u32_e32 v150, 54, v136
	v_ashrrev_i32_e32 v151, 31, v150
	v_mul_lo_u32 v152, s16, v151
	v_mul_lo_u32 v153, s17, v150
	v_mad_u64_u32 v[150:151], s[34:35], s16, v150, 0
	v_add3_u32 v151, v151, v152, v153
	v_add_u32_e32 v152, 56, v136
	v_ashrrev_i32_e32 v153, 31, v152
	v_mul_lo_u32 v154, s16, v153
	v_mul_lo_u32 v155, s17, v152
	v_mad_u64_u32 v[152:153], s[34:35], s16, v152, 0
	v_add3_u32 v153, v153, v154, v155
	v_add_u32_e32 v154, 58, v136
	v_ashrrev_i32_e32 v155, 31, v154
	v_mul_lo_u32 v156, s16, v155
	v_mul_lo_u32 v157, s17, v154
	v_mad_u64_u32 v[154:155], s[34:35], s16, v154, 0
	v_add3_u32 v155, v155, v156, v157
	v_add_u32_e32 v156, 60, v136
	v_ashrrev_i32_e32 v157, 31, v156
	v_mul_lo_u32 v158, s16, v157
	v_mul_lo_u32 v159, s17, v156
	v_mad_u64_u32 v[156:157], s[34:35], s16, v156, 0
	v_add3_u32 v157, v157, v158, v159
	v_add_u32_e32 v158, 62, v136
	v_ashrrev_i32_e32 v159, 31, v158
	v_mul_lo_u32 v160, s16, v159
	v_mul_lo_u32 v161, s17, v158
	v_mad_u64_u32 v[158:159], s[16:17], s16, v158, 0
	v_lshl_add_u64 v[98:99], v[98:99], 2, v[96:97]
	v_lshl_add_u64 v[100:101], v[100:101], 2, v[96:97]
	v_lshl_add_u64 v[102:103], v[102:103], 2, v[96:97]
	v_add3_u32 v159, v159, v160, v161
	v_lshl_add_u64 v[150:151], v[150:151], 2, v[96:97]
	v_lshl_add_u64 v[152:153], v[152:153], 2, v[96:97]
	v_lshl_add_u64 v[154:155], v[154:155], 2, v[96:97]
	v_lshl_add_u64 v[156:157], v[156:157], 2, v[96:97]
	v_lshl_add_u64 v[158:159], v[158:159], 2, v[96:97]
	global_load_dword v96, v[98:99], off sc1 nt
	global_load_dword v97, v[100:101], off sc1 nt
	s_nop 0
	global_load_dword v98, v[102:103], off sc1 nt
	global_load_dword v99, v[150:151], off sc1 nt
	global_load_dword v100, v[152:153], off sc1 nt
	global_load_dword v101, v[154:155], off sc1 nt
	s_nop 0
	global_load_dword v102, v[156:157], off sc1 nt
	global_load_dword v103, v[158:159], off sc1 nt
	s_cmp_eq_u64 s[22:23], 0
	s_mov_b64 s[16:17], 0
	s_cbranch_scc1 .LBB0_299
	v_lshl_add_u64 v[136:137], v[136:137], 2, s[22:23]
	global_load_dword v10, v[136:137], off sc1 nt
	global_load_dword v11, v[136:137], off offset:8 sc1 nt
	global_load_dword v12, v[136:137], off offset:16 sc1 nt
	global_load_dword v13, v[136:137], off offset:24 sc1 nt
	global_load_dword v14, v[136:137], off offset:32 sc1 nt
	global_load_dword v15, v[136:137], off offset:40 sc1 nt
	global_load_dword v16, v[136:137], off offset:48 sc1 nt
	global_load_dword v17, v[136:137], off offset:56 sc1 nt
	global_load_dword v18, v[136:137], off offset:64 sc1 nt
	global_load_dword v19, v[136:137], off offset:72 sc1 nt
	global_load_dword v20, v[136:137], off offset:80 sc1 nt
	global_load_dword v21, v[136:137], off offset:88 sc1 nt
	global_load_dword v22, v[136:137], off offset:96 sc1 nt
	global_load_dword v23, v[136:137], off offset:104 sc1 nt
	global_load_dword v24, v[136:137], off offset:112 sc1 nt
	global_load_dword v25, v[136:137], off offset:120 sc1 nt
	global_load_dword v26, v[136:137], off offset:128 sc1 nt
	global_load_dword v27, v[136:137], off offset:136 sc1 nt
	global_load_dword v28, v[136:137], off offset:144 sc1 nt
	global_load_dword v29, v[136:137], off offset:152 sc1 nt
	global_load_dword v30, v[136:137], off offset:160 sc1 nt
	global_load_dword v31, v[136:137], off offset:168 sc1 nt
	global_load_dword v32, v[136:137], off offset:176 sc1 nt
	global_load_dword v33, v[136:137], off offset:184 sc1 nt
	global_load_dword v34, v[136:137], off offset:192 sc1 nt
	global_load_dword v35, v[136:137], off offset:200 sc1 nt
	global_load_dword v36, v[136:137], off offset:208 sc1 nt
	global_load_dword v37, v[136:137], off offset:216 sc1 nt
	global_load_dword v38, v[136:137], off offset:224 sc1 nt
	global_load_dword v39, v[136:137], off offset:232 sc1 nt
	global_load_dword v40, v[136:137], off offset:240 sc1 nt
	global_load_dword v41, v[136:137], off offset:248 sc1 nt
	s_mov_b64 s[16:17], s[22:23]

.LBB0_377:
	s_mov_b32 s64, s100
	s_cmp_gt_i32 s67, 5
	v_readlane_b32 s4, v253, 41
	s_cselect_b64 s[0:1], -1, 0
	v_readlane_b32 s18, v253, 55
	v_readlane_b32 s19, v253, 56
	s_and_b64 s[2:3], s[30:31], s[0:1]
	v_readlane_b32 s14, v253, 51
	v_readlane_b32 s15, v253, 52
	v_readlane_b32 s16, v253, 53
	v_readlane_b32 s17, v253, 54
	s_mov_b64 s[50:51], s[18:19]
	v_readlane_b32 s88, v253, 39
	v_readlane_b32 s90, v253, 21
	s_andn2_b64 vcc, exec, s[2:3]
	s_mov_b64 s[48:49], s[16:17]
	s_mov_b64 s[46:47], s[14:15]
	v_readlane_b32 s89, v253, 40
	v_readlane_b32 s91, v253, 22
	v_readlane_b32 s5, v253, 42
	v_readlane_b32 s6, v253, 43
	v_readlane_b32 s7, v253, 44
	v_readlane_b32 s8, v253, 45
	v_readlane_b32 s9, v253, 46
	v_readlane_b32 s10, v253, 47
	v_readlane_b32 s11, v253, 48
	v_readlane_b32 s12, v253, 49
	v_readlane_b32 s13, v253, 50
	s_cbranch_vccnz .LBB0_435
	s_waitcnt vmcnt(0)
	s_waitcnt vmcnt(0) lgkmcnt(0)
	s_barrier
	s_and_saveexec_b64 s[2:3], s[96:97]
	s_cbranch_execz .LBB0_434
	s_add_i32 s4, 0, 0x26960
	v_mov_b32_e32 v1, s4
	s_waitcnt vmcnt(0) expcnt(0) lgkmcnt(0)
	ds_read_b32 v3, v1
	s_add_i32 s4, 0, 0x26964
	v_mov_b32_e32 v1, s4
	ds_read_b32 v1, v1
	s_waitcnt lgkmcnt(1)
	v_cmp_ne_u32_e32 vcc, 0, v3
	s_cbranch_vccnz .LBB0_394
	v_readlane_b32 s4, v253, 0
	v_readlane_b32 s5, v253, 1
	s_load_dwordx2 s[8:9], s[4:5], 0x4
	s_add_u32 s4, s50, 0x4200
	s_addc_u32 s5, s51, 0
	s_add_u32 s6, s50, 0x4400
	s_addc_u32 s7, s51, 0
	s_waitcnt lgkmcnt(0)
	s_mul_i32 s33, s8, s92
	s_add_u32 s8, s50, 0x4500
	s_mul_i32 s33, s33, s9
	s_addc_u32 s9, s51, 0
	s_add_u32 s10, s50, 0x4600
	s_addc_u32 s11, s51, 0
	s_add_u32 s12, s50, 0x4700
	s_addc_u32 s13, s51, 0
	s_add_u32 s14, s50, 0x4800
	s_addc_u32 s15, s51, 0
	s_add_u32 s16, s50, 0x4900
	s_addc_u32 s17, s51, 0
	s_add_u32 s18, s50, 0x4a00
	s_addc_u32 s19, s51, 0
	s_add_u32 s20, s50, 0x4b00
	s_addc_u32 s21, s51, 0
	s_add_u32 s22, s50, 0x4c00
	s_addc_u32 s23, s51, 0
	s_add_u32 s30, s50, 0x4d00
	s_addc_u32 s31, s51, 0
	s_add_u32 s34, s50, 0x4e00
	s_addc_u32 s35, s51, 0
	s_add_u32 s36, s50, 0x4f00
	s_addc_u32 s37, s51, 0
	s_add_u32 s38, s50, 0x5000
	s_addc_u32 s39, s51, 0
	s_add_u32 s40, s50, 0x5100
	s_addc_u32 s41, s51, 0
	s_add_u32 s42, s50, 0x5200
	s_addc_u32 s43, s51, 0
	s_add_u32 s44, s50, 0x5300
	s_addc_u32 s45, s51, 0
	s_mov_b32 s52, 1
	v_mov_b32_e32 v17, 0
	s_branch .LBB0_382

	.amdhsa_kernel _Z7hyb_fwd4Args
		.amdhsa_group_segment_fixed_size 0
		.amdhsa_private_segment_fixed_size 0
		.amdhsa_kernarg_size 400
		.amdhsa_user_sgpr_count 2
		.amdhsa_user_sgpr_dispatch_ptr 0
		.amdhsa_user_sgpr_queue_ptr 0
		.amdhsa_user_sgpr_kernarg_segment_ptr 1
		.amdhsa_user_sgpr_dispatch_id 0
		.amdhsa_user_sgpr_kernarg_preload_length 0
		.amdhsa_user_sgpr_kernarg_preload_offset 0
		.amdhsa_user_sgpr_private_segment_size 0
		.amdhsa_uses_dynamic_stack 0
		.amdhsa_enable_private_segment 0
		.amdhsa_system_sgpr_workgroup_id_x 1
		.amdhsa_system_sgpr_workgroup_id_y 0
		.amdhsa_system_sgpr_workgroup_id_z 0
		.amdhsa_system_sgpr_workgroup_info 0
		.amdhsa_system_vgpr_workitem_id 0
		.amdhsa_next_free_vgpr 254
		.amdhsa_next_free_sgpr 102
		.amdhsa_accum_offset 256
		.amdhsa_reserve_vcc 1
		.amdhsa_float_round_mode_32 0
		.amdhsa_float_round_mode_16_64 0
		.amdhsa_float_denorm_mode_32 3
		.amdhsa_float_denorm_mode_16_64 3
		.amdhsa_dx10_clamp 1
		.amdhsa_ieee_mode 1
		.amdhsa_fp16_overflow 0
		.amdhsa_tg_split 0
		.amdhsa_exception_fp_ieee_invalid_op 0
		.amdhsa_exception_fp_denorm_src 0
		.amdhsa_exception_fp_ieee_div_zero 0
		.amdhsa_exception_fp_ieee_overflow 0
		.amdhsa_exception_fp_ieee_underflow 0
		.amdhsa_exception_fp_ieee_inexact 0
		.amdhsa_exception_int_div_zero 0
	.end_amdhsa_kernel

amdhsa.kernels:
  - .agpr_count:     0
    .args:
      - .offset:         0
        .size:           144
        .value_kind:     by_value
      - .offset:         144
        .size:           4
        .value_kind:     hidden_block_count_x
      - .offset:         148
        .size:           4
        .value_kind:     hidden_block_count_y
      - .offset:         152
        .size:           4
        .value_kind:     hidden_block_count_z
      - .offset:         156
        .size:           2
        .value_kind:     hidden_group_size_x
      - .offset:         158
        .size:           2
        .value_kind:     hidden_group_size_y
      - .offset:         160
        .size:           2
        .value_kind:     hidden_group_size_z
      - .offset:         162
        .size:           2
        .value_kind:     hidden_remainder_x
      - .offset:         164
        .size:           2
        .value_kind:     hidden_remainder_y
      - .offset:         166
        .size:           2
        .value_kind:     hidden_remainder_z
      - .offset:         184
        .size:           8
        .value_kind:     hidden_global_offset_x
      - .offset:         192
        .size:           8
        .value_kind:     hidden_global_offset_y
      - .offset:         200
        .size:           8
        .value_kind:     hidden_global_offset_z
      - .offset:         208
        .size:           2
        .value_kind:     hidden_grid_dims
      - .offset:         264
        .size:           4
        .value_kind:     hidden_dynamic_lds_size
    .group_segment_fixed_size: 0
    .kernarg_segment_align: 8
    .kernarg_segment_size: 400
    .language:       OpenCL C
    .language_version:
      - 2
      - 0
    .max_flat_workgroup_size: 512
    .name:           _Z7hyb_fwd4Args
    .private_segment_fixed_size: 0
    .sgpr_count:     108
    .sgpr_spill_count: 68
    .symbol:         _Z7hyb_fwd4Args.kd
    .uniform_work_group_size: 1
    .uses_dynamic_stack: false
    .vgpr_count:     254
    .vgpr_spill_count: 0
    .wavefront_size: 64
